# stagger at P7 entry: odd workgroup groups wait 4 x s_sleep 127 (about one epilogue burst) so P7/P8/P9 epilogue memory bursts of the two halves interleave; relies on the group-local syncs
# baseline (speedup 1.0000x reference)
.LBB0_486:
	s_or_b64 exec, exec, s[4:5]
	s_bitcmp1_b32 s2, 0
	s_cbranch_scc0 .Lstg_skip
	s_movk_i32 s74, 4
.Lstg_loop:
	s_sleep 127
	s_sub_u32 s74, s74, 1
	s_cmp_lg_u32 s74, 0
	s_cbranch_scc1 .Lstg_loop
.Lstg_skip:
	v_mov_b32_e32 v0, v254
	v_mov_b32_e32 v8, v254
	s_cmpk_lt_i32 s2, 0x200
	s_barrier
	s_cselect_b64 s[6:7], -1, 0
	s_cmpk_gt_i32 s2, 0x1ff
	v_readfirstlane_b32 s8, v8
	s_cbranch_scc1 .LBB0_489
	s_lshr_b32 s0, s3, 29
	s_add_i32 s0, s2, s0
	s_and_b32 s1, s0, -8
	s_sub_i32 s1, s2, s1
	s_cmp_gt_i32 s1, -1
	s_cbranch_scc0 .LBB0_490
	s_lshl_b32 s9, s1, 6
	s_cbranch_execz .LBB0_491
	s_branch .LBB0_492
